# speedup vs baseline: 1.0124x; 1.0124x over previous
; __device__ __forceinline__ void qkt8(f32x16& p0, f32x16& p1, const char* Ks, const i32x8* q8, int r32, int hi) {
;     const int s127 = 127, s124 = 124;
;     const int sw0 = (r32 >> 1) & 7, sw1 = ((32 + r32) >> 1) & 7; const char* rp0 = Ks + r32 * 128; const char* rp1 = Ks + (32 + r32) * 128;
;     ...
;     {   i32x8 ka = K8LD(rp0, 0, sw0), kb = K8LD(rp1, 0, sw1);
;         asm volatile("s_waitcnt lgkmcnt(0)" ::: "memory");
;         asm volatile("v_mfma_scale_f32_32x32x64_f8f6f4 %0, %1, %2, -4.0, %3, %4 op_sel_hi:[0,0,0]" : "=&v"(p0) : "v"(ka), "v"(q8[0]), "v"(s127), "v"(s124));
;         asm volatile("v_mfma_scale_f32_32x32x64_f8f6f4 %0, %1, %2, -4.0, %3, %4 op_sel_hi:[0,0,0]" : "=&v"(p1) : "v"(kb), "v"(q8[0]), "v"(s127), "v"(s124)); }
;     {   i32x8 ka = K8LD(rp0, 1, sw0), kb = K8LD(rp1, 1, sw1);
;         asm volatile("s_waitcnt lgkmcnt(0)" ::: "memory");
;         asm volatile("v_mfma_scale_f32_32x32x64_f8f6f4 %0, %1, %2, %0, %3, %4 op_sel_hi:[0,0,0]" : "+v"(p0) : "v"(ka), "v"(q8[1]), "v"(s127), "v"(s124));
;         asm volatile("v_mfma_scale_f32_32x32x64_f8f6f4 %0, %1, %2, %0, %3, %4 op_sel_hi:[0,0,0]" : "+v"(p1) : "v"(kb), "v"(q8[1]), "v"(s127), "v"(s124)); }
; }
; __device__ __forceinline__ void finishSM8(f32x16& p0, f32x16& p1, float& l_reg, i32x8& pa) {
;     for (int r = 0; r < 16; ++r) p1[r] = __builtin_amdgcn_exp2f(p1[r]);
;     float ps = 0; for (int r = 0; r < 16; ++r) ps += p0[r]; for (int r = 0; r < 16; ++r) ps += p1[r];
;     l_reg += ps;
; #pragma unroll
;     for (int q = 0; q < 4; ++q) { int v = 0; v = __builtin_amdgcn_cvt_pk_bf8_f32(p0[4 * q], p0[4 * q + 1], v, false); v = __builtin_amdgcn_cvt_pk_bf8_f32(p0[4 * q + 2], p0[4 * q + 3], v, true); pa[q] = v; }
; #pragma unroll
;     for (int q = 0; q < 4; ++q) { int v = 0; v = __builtin_amdgcn_cvt_pk_bf8_f32(p1[4 * q], p1[4 * q + 1], v, false); v = __builtin_amdgcn_cvt_pk_bf8_f32(p1[4 * q + 2], p1[4 * q + 3], v, true); pa[4 + q] = v; }
; }
; template <bool EXPQ>
; __device__ __forceinline__ void pv8(f32x16* o, const char* Vs, const i32x8& pa, int r32, int hi, f32x16& pe) {
;     const int s127 = 127; const char* vp = Vs + r32 * 80 + hi * 32;
;     {   const i32x8 v0 = *(const i32x8*)(vp), v1 = *(const i32x8*)(vp + 32 * 80);
;         asm volatile("s_waitcnt lgkmcnt(0)" ::: "memory");
.LBB0_1027:
	s_mov_b32 s47, s35
	s_mov_b32 s35, s44
	s_lshl_b32 s49, s47, 14
	s_lshl_b32 s50, s44, 14
	v_add_u32_e32 v252, s49, v201
	v_add_u32_e32 v253, s50, v207
	v_add_u32_e32 v248, v252, v202
	v_add_u32_e32 v249, v252, v203
	v_add_u32_e32 v250, v252, v205
	v_add_u32_e32 v251, v252, v206
	ds_read_b128 v[208:211], v248 offset:49152
	ds_read_b128 v[212:215], v249 offset:49152
	ds_read_b128 v[216:219], v248 offset:53248
	ds_read_b128 v[220:223], v249 offset:53248
	ds_read_b128 v[224:227], v250 offset:49152
	ds_read_b128 v[228:231], v251 offset:49152
	ds_read_b128 v[232:235], v250 offset:53248
	ds_read_b128 v[236:239], v251 offset:53248
	ds_read_b128 v[136:139], v253
	ds_read_b128 v[140:143], v253 offset:16
	ds_read_b128 v[240:243], v253 offset:2560
	ds_read_b128 v[244:247], v253 offset:2576
	v_cvt_pk_bf8_f32 v128, v64, v65
	v_cvt_pk_bf8_f32 v129, v68, v69
	v_cvt_pk_bf8_f32 v130, v72, v73
	v_cvt_pk_bf8_f32 v131, v76, v77
	v_exp_f32_e32 v80, v80
	v_exp_f32_e32 v81, v81
	s_waitcnt lgkmcnt(10)
	v_mfma_scale_f32_32x32x64_f8f6f4 v[96:111], v[208:215], v[152:159], -4.0, v189, v190 op_sel_hi:[0,0,0]
	v_cvt_pk_bf8_f32 v128, v66, v67 op_sel:[0,0,1]
	v_cvt_pk_bf8_f32 v129, v70, v71 op_sel:[0,0,1]
	ds_read_b128 v[208:211], v253 offset:5120
	ds_read_b128 v[212:215], v253 offset:5136
	v_cvt_pk_bf8_f32 v130, v74, v75 op_sel:[0,0,1]
	v_cvt_pk_bf8_f32 v131, v78, v79 op_sel:[0,0,1]
	v_exp_f32_e32 v84, v84
	v_exp_f32_e32 v85, v85
	v_exp_f32_e32 v88, v88
	s_waitcnt lgkmcnt(10)
	v_mfma_scale_f32_32x32x64_f8f6f4 v[112:127], v[216:223], v[152:159], -4.0, v189, v190 op_sel_hi:[0,0,0]
	v_exp_f32_e32 v89, v89
	v_exp_f32_e32 v92, v92
	v_exp_f32_e32 v93, v93
	ds_read_b128 v[216:219], v253 offset:7680
	ds_read_b128 v[220:223], v253 offset:7696
	v_exp_f32_e32 v82, v82
	v_exp_f32_e32 v83, v83
	v_exp_f32_e32 v86, v86
	v_exp_f32_e32 v87, v87
	v_exp_f32_e32 v90, v90
	s_waitcnt lgkmcnt(10)
	v_mfma_scale_f32_32x32x64_f8f6f4 v[96:111], v[224:231], v[144:151], v[96:111], v189, v190 op_sel_hi:[0,0,0]
	v_exp_f32_e32 v91, v91
	v_exp_f32_e32 v94, v94
	v_exp_f32_e32 v95, v95
	v_cvt_pk_bf8_f32 v132, v80, v81
	v_cvt_pk_bf8_f32 v133, v84, v85
	v_cvt_pk_bf8_f32 v134, v88, v89
	v_cvt_pk_bf8_f32 v135, v92, v93
	s_waitcnt lgkmcnt(8)
	v_mfma_scale_f32_32x32x64_f8f6f4 v[112:127], v[232:239], v[144:151], v[112:127], v189, v190 op_sel_hi:[0,0,0]
	v_cvt_pk_bf8_f32 v132, v82, v83 op_sel:[0,0,1]
	v_cvt_pk_bf8_f32 v133, v86, v87 op_sel:[0,0,1]
	v_cvt_pk_bf8_f32 v134, v90, v91 op_sel:[0,0,1]
	v_cvt_pk_bf8_f32 v135, v94, v95 op_sel:[0,0,1]
	v_lshl_add_u64 v[186:187], s[28:29], 0, v[182:183]
	v_add_co_u32_e32 v250, vcc, s62, v186
	v_lshl_add_u64 v[184:185], s[28:29], 0, v[180:181]
	v_add_f32_e32 v248, v64, v65
	v_addc_co_u32_e32 v251, vcc, 0, v187, vcc
	v_add_co_u32_e32 v252, vcc, s63, v184
	v_add_f32_e32 v249, v80, v81
	v_add_f32_e32 v248, v66, v248
	v_addc_co_u32_e32 v253, vcc, 0, v185, vcc
	global_load_dwordx4 v[172:175], v[250:251], off
	global_load_dwordx4 v[168:171], v[252:253], off
	v_add_f32_e32 v249, v82, v249
	s_waitcnt lgkmcnt(6)
	v_mfma_f32_32x32x64_f8f6f4 v[0:15], v[128:135], v[136:143], v[0:15] cbsz:1
	v_add_f32_e32 v248, v67, v248
	v_add_f32_e32 v249, v83, v249
	v_add_f32_e32 v248, v68, v248
	v_add_f32_e32 v249, v84, v249
	v_add_f32_e32 v248, v69, v248
	v_add_f32_e32 v249, v85, v249
	v_add_f32_e32 v248, v70, v248
	v_add_f32_e32 v249, v86, v249
	v_add_f32_e32 v248, v71, v248
	v_add_f32_e32 v249, v87, v249
	v_add_f32_e32 v248, v72, v248
	v_add_f32_e32 v249, v88, v249
	v_add_f32_e32 v248, v73, v248
	v_add_f32_e32 v249, v89, v249
	s_waitcnt lgkmcnt(4)
	v_mfma_f32_32x32x64_f8f6f4 v[16:31], v[128:135], v[240:247], v[16:31] cbsz:1
	s_lshl_b32 s44, s46, 14
	v_add_u32_e32 v250, s44, v199
	s_add_i32 s48, s44, 0
	v_add_u32_e32 v251, s48, v198
	v_add_u32_e32 v252, s48, v200
	s_waitcnt vmcnt(2)
	ds_write_b128 v250, v[164:167]
	ds_write_b64 v251, v[160:161] offset:49152
	ds_write_b64 v252, v[162:163] offset:49152
	v_add_f32_e32 v248, v74, v248
	v_add_f32_e32 v249, v90, v249
	v_add_f32_e32 v248, v75, v248
	v_add_f32_e32 v249, v91, v249
	v_add_f32_e32 v248, v76, v248
	v_add_f32_e32 v249, v92, v249
	v_exp_f32_e32 v96, v96
	v_exp_f32_e32 v97, v97
	v_exp_f32_e32 v98, v98
	v_exp_f32_e32 v99, v99
	s_waitcnt lgkmcnt(5)
	v_mfma_f32_32x32x64_f8f6f4 v[32:47], v[128:135], v[208:215], v[32:47] cbsz:1
	v_add_f32_e32 v248, v77, v248
	v_add_f32_e32 v249, v93, v249
	v_add_f32_e32 v248, v78, v248
	v_add_f32_e32 v249, v94, v249
	v_exp_f32_e32 v100, v100
	v_exp_f32_e32 v101, v101
	v_exp_f32_e32 v102, v102
	v_exp_f32_e32 v103, v103
	v_exp_f32_e32 v104, v104
	v_exp_f32_e32 v105, v105
	s_waitcnt lgkmcnt(3)
	v_mfma_f32_32x32x64_f8f6f4 v[48:63], v[128:135], v[216:223], v[48:63] cbsz:1
	v_add_f32_e32 v248, v79, v248
	v_add_f32_e32 v249, v95, v249
	v_add_f32_e32 v178, v178, v248
	v_add_f32_e32 v178, v178, v249
	v_exp_f32_e32 v106, v106
	v_exp_f32_e32 v107, v107
	v_exp_f32_e32 v108, v108
	v_exp_f32_e32 v109, v109
	v_exp_f32_e32 v110, v110
	v_exp_f32_e32 v111, v111
	s_waitcnt lgkmcnt(0)
	s_barrier
; __device__ __forceinline__ void qkt8(f32x16& p0, f32x16& p1, const char* Ks, const i32x8* q8, int r32, int hi) {
;     const int s127 = 127, s124 = 124;
;     const int sw0 = (r32 >> 1) & 7, sw1 = ((32 + r32) >> 1) & 7; const char* rp0 = Ks + r32 * 128; const char* rp1 = Ks + (32 + r32) * 128;
;     ...
;     {   i32x8 ka = K8LD(rp0, 0, sw0), kb = K8LD(rp1, 0, sw1);
;         asm volatile("s_waitcnt lgkmcnt(0)" ::: "memory");
;         asm volatile("v_mfma_scale_f32_32x32x64_f8f6f4 %0, %1, %2, -4.0, %3, %4 op_sel_hi:[0,0,0]" : "=&v"(p0) : "v"(ka), "v"(q8[0]), "v"(s127), "v"(s124));
;         asm volatile("v_mfma_scale_f32_32x32x64_f8f6f4 %0, %1, %2, -4.0, %3, %4 op_sel_hi:[0,0,0]" : "=&v"(p1) : "v"(kb), "v"(q8[0]), "v"(s127), "v"(s124)); }
;     {   i32x8 ka = K8LD(rp0, 1, sw0), kb = K8LD(rp1, 1, sw1);
;         asm volatile("s_waitcnt lgkmcnt(0)" ::: "memory");
;         asm volatile("v_mfma_scale_f32_32x32x64_f8f6f4 %0, %1, %2, %0, %3, %4 op_sel_hi:[0,0,0]" : "+v"(p0) : "v"(ka), "v"(q8[1]), "v"(s127), "v"(s124));
;         asm volatile("v_mfma_scale_f32_32x32x64_f8f6f4 %0, %1, %2, %0, %3, %4 op_sel_hi:[0,0,0]" : "+v"(p1) : "v"(kb), "v"(q8[1]), "v"(s127), "v"(s124)); }
; }
; __device__ __forceinline__ void finishSM8(f32x16& p0, f32x16& p1, float& l_reg, i32x8& pa) {
;     for (int r = 0; r < 16; ++r) p1[r] = __builtin_amdgcn_exp2f(p1[r]);
;     float ps = 0; for (int r = 0; r < 16; ++r) ps += p0[r]; for (int r = 0; r < 16; ++r) ps += p1[r];
;     l_reg += ps;
; #pragma unroll
;     for (int q = 0; q < 4; ++q) { int v = 0; v = __builtin_amdgcn_cvt_pk_bf8_f32(p0[4 * q], p0[4 * q + 1], v, false); v = __builtin_amdgcn_cvt_pk_bf8_f32(p0[4 * q + 2], p0[4 * q + 3], v, true); pa[q] = v; }
; #pragma unroll
;     for (int q = 0; q < 4; ++q) { int v = 0; v = __builtin_amdgcn_cvt_pk_bf8_f32(p1[4 * q], p1[4 * q + 1], v, false); v = __builtin_amdgcn_cvt_pk_bf8_f32(p1[4 * q + 2], p1[4 * q + 3], v, true); pa[4 + q] = v; }
; }
; template <bool EXPQ>
; __device__ __forceinline__ void pv8(f32x16* o, const char* Vs, const i32x8& pa, int r32, int hi, f32x16& pe) {
;     const int s127 = 127; const char* vp = Vs + r32 * 80 + hi * 32;
;     {   const i32x8 v0 = *(const i32x8*)(vp), v1 = *(const i32x8*)(vp + 32 * 80);
;         asm volatile("s_waitcnt lgkmcnt(0)" ::: "memory");
	v_add_u32_e32 v252, s48, v201
	v_add_u32_e32 v253, s49, v207
	s_add_i32 s49, s50, 0
	v_add_u32_e32 v248, v252, v202
	v_add_u32_e32 v249, v252, v203
	v_add_u32_e32 v250, v252, v205
	v_add_u32_e32 v251, v252, v206
	ds_read_b128 v[208:211], v248 offset:49152
	ds_read_b128 v[212:215], v249 offset:49152
	ds_read_b128 v[216:219], v248 offset:53248
	ds_read_b128 v[220:223], v249 offset:53248
	ds_read_b128 v[224:227], v250 offset:49152
	ds_read_b128 v[228:231], v251 offset:49152
	ds_read_b128 v[232:235], v250 offset:53248
	ds_read_b128 v[236:239], v251 offset:53248
	ds_read_b128 v[136:139], v253
	ds_read_b128 v[140:143], v253 offset:16
	ds_read_b128 v[240:243], v253 offset:2560
	ds_read_b128 v[244:247], v253 offset:2576
	v_cvt_pk_bf8_f32 v128, v96, v97
	v_cvt_pk_bf8_f32 v129, v100, v101
	v_cvt_pk_bf8_f32 v130, v104, v105
	v_cvt_pk_bf8_f32 v131, v108, v109
	v_exp_f32_e32 v112, v112
	v_exp_f32_e32 v113, v113
	s_waitcnt lgkmcnt(10)
	v_mfma_scale_f32_32x32x64_f8f6f4 v[64:79], v[208:215], v[152:159], -4.0, v189, v190 op_sel_hi:[0,0,0]
	v_cvt_pk_bf8_f32 v128, v98, v99 op_sel:[0,0,1]
	v_cvt_pk_bf8_f32 v129, v102, v103 op_sel:[0,0,1]
	ds_read_b128 v[208:211], v253 offset:5120
	ds_read_b128 v[212:215], v253 offset:5136
	v_cvt_pk_bf8_f32 v130, v106, v107 op_sel:[0,0,1]
	v_cvt_pk_bf8_f32 v131, v110, v111 op_sel:[0,0,1]
	v_exp_f32_e32 v116, v116
	v_exp_f32_e32 v117, v117
	v_exp_f32_e32 v120, v120
	s_waitcnt lgkmcnt(10)
	v_mfma_scale_f32_32x32x64_f8f6f4 v[80:95], v[216:223], v[152:159], -4.0, v189, v190 op_sel_hi:[0,0,0]
	v_exp_f32_e32 v121, v121
	v_exp_f32_e32 v124, v124
	v_exp_f32_e32 v125, v125
	ds_read_b128 v[216:219], v253 offset:7680
	ds_read_b128 v[220:223], v253 offset:7696
	v_exp_f32_e32 v114, v114
	v_exp_f32_e32 v115, v115
	v_exp_f32_e32 v118, v118
	v_exp_f32_e32 v119, v119
	v_exp_f32_e32 v122, v122
	s_waitcnt lgkmcnt(10)
	v_mfma_scale_f32_32x32x64_f8f6f4 v[64:79], v[224:231], v[144:151], v[64:79], v189, v190 op_sel_hi:[0,0,0]
	v_exp_f32_e32 v123, v123
	v_exp_f32_e32 v126, v126
	v_exp_f32_e32 v127, v127
	v_cvt_pk_bf8_f32 v132, v112, v113
	v_cvt_pk_bf8_f32 v133, v116, v117
	v_cvt_pk_bf8_f32 v134, v120, v121
	v_cvt_pk_bf8_f32 v135, v124, v125
	s_waitcnt lgkmcnt(8)
	v_mfma_scale_f32_32x32x64_f8f6f4 v[80:95], v[232:239], v[144:151], v[80:95], v189, v190 op_sel_hi:[0,0,0]
	v_cvt_pk_bf8_f32 v132, v114, v115 op_sel:[0,0,1]
	v_cvt_pk_bf8_f32 v133, v118, v119 op_sel:[0,0,1]
	v_cvt_pk_bf8_f32 v134, v122, v123 op_sel:[0,0,1]
	v_cvt_pk_bf8_f32 v135, v126, v127 op_sel:[0,0,1]
	s_cmp_ge_u32 s3, s69
	s_cselect_b64 s[44:45], -1, 0
	s_and_b64 vcc, exec, s[44:45]
	s_cbranch_vccnz .Lf3_skip
	v_add_co_u32_e32 v160, vcc, 0x49730000, v186
	v_add_f32_e32 v248, v96, v97
	v_add_f32_e32 v249, v112, v113
	v_addc_co_u32_e32 v161, vcc, 0, v187, vcc
	v_add_co_u32_e32 v162, vcc, 0x48b30000, v184
	v_add_f32_e32 v248, v98, v248
	v_add_f32_e32 v249, v114, v249
	v_addc_co_u32_e32 v163, vcc, 0, v185, vcc
	global_load_dwordx4 v[164:167], v[160:161], off
	s_nop 0
	global_load_dwordx4 v[160:163], v[162:163], off
	s_branch .Lf3_sedone
.Lf3_skip:
	v_add_f32_e32 v248, v96, v97
	v_add_f32_e32 v249, v112, v113
	v_add_f32_e32 v248, v98, v248
	v_add_f32_e32 v249, v114, v249
.Lf3_sedone:
	s_waitcnt lgkmcnt(6)
	v_mfma_f32_32x32x64_f8f6f4 v[0:15], v[128:135], v[136:143], v[0:15] cbsz:1
	v_add_f32_e32 v248, v99, v248
	v_add_f32_e32 v249, v115, v249
	v_add_f32_e32 v248, v100, v248
	v_add_f32_e32 v249, v116, v249
	v_add_f32_e32 v248, v101, v248
	v_add_f32_e32 v249, v117, v249
	v_add_f32_e32 v248, v102, v248
	v_add_f32_e32 v249, v118, v249
	v_add_f32_e32 v248, v103, v248
	v_add_f32_e32 v249, v119, v249
	v_add_f32_e32 v248, v104, v248
	v_add_f32_e32 v249, v120, v249
	v_add_f32_e32 v248, v105, v248
	v_add_f32_e32 v249, v121, v249
	s_waitcnt lgkmcnt(4)
	v_mfma_f32_32x32x64_f8f6f4 v[16:31], v[128:135], v[240:247], v[16:31] cbsz:1
	v_add_u32_e32 v250, s50, v199
	v_add_u32_e32 v251, s49, v198
	v_add_u32_e32 v252, s49, v200
	s_and_b64 vcc, exec, s[44:45]
	s_cbranch_vccnz .Lf3_lastw
	s_waitcnt vmcnt(2)
.Lf3_wr:
	ds_write_b128 v250, v[172:175]
	ds_write_b64 v251, v[168:169] offset:49152
	ds_write_b64 v252, v[170:171] offset:49152
	v_add_f32_e32 v248, v106, v248
	v_add_f32_e32 v249, v122, v249
	v_add_f32_e32 v248, v107, v248
	v_add_f32_e32 v249, v123, v249
	v_add_f32_e32 v248, v108, v248
	v_add_f32_e32 v249, v124, v249
	v_exp_f32_e32 v64, v64
	v_exp_f32_e32 v65, v65
	v_exp_f32_e32 v66, v66
	v_exp_f32_e32 v67, v67
	s_waitcnt lgkmcnt(5)
	v_mfma_f32_32x32x64_f8f6f4 v[32:47], v[128:135], v[208:215], v[32:47] cbsz:1
	v_add_f32_e32 v248, v109, v248
	v_add_f32_e32 v249, v125, v249
	v_add_f32_e32 v248, v110, v248
	v_add_f32_e32 v249, v126, v249
	v_exp_f32_e32 v68, v68
	v_exp_f32_e32 v69, v69
	v_exp_f32_e32 v70, v70
	v_exp_f32_e32 v71, v71
	v_exp_f32_e32 v72, v72
	v_exp_f32_e32 v73, v73
	s_waitcnt lgkmcnt(3)
	v_mfma_f32_32x32x64_f8f6f4 v[48:63], v[128:135], v[216:223], v[48:63] cbsz:1
	v_add_f32_e32 v248, v111, v248
	v_add_f32_e32 v249, v127, v249
	v_add_f32_e32 v178, v178, v248
	v_add_f32_e32 v178, v178, v249
	v_exp_f32_e32 v74, v74
	v_exp_f32_e32 v75, v75
	v_exp_f32_e32 v76, v76
	v_exp_f32_e32 v77, v77
	v_exp_f32_e32 v78, v78
	v_exp_f32_e32 v79, v79
	v_lshl_add_u64 v[180:181], v[180:181], 0, s[22:23]
	v_lshl_add_u64 v[182:183], v[182:183], 0, s[22:23]
	s_add_i32 s3, s3, 2
	s_and_b64 vcc, exec, s[44:45]
	s_waitcnt lgkmcnt(0)
	s_barrier
	s_cbranch_vccnz .LBB0_1031
	s_mov_b32 s44, s46
	s_mov_b32 s46, s47
	s_branch .LBB0_1027
